# attention loop: score and PV MFMAs reordered into accumulate chains where operands are already resident (four adjacent swaps / one hoist), on top of the K-loop alternating-chain order
# baseline (speedup 1.0000x reference)
.Lqpf_skip:
	s_cmp_gt_u32 s13, 9
	s_waitcnt lgkmcnt(0)
	s_barrier
	s_cbranch_scc1 .LBB0_1072
	s_add_i32 s26, s21, s22
	s_cmp_lg_u32 s13, 9
	s_cselect_b32 s27, s26, 0xfffffd80
	v_add_u32_e32 v152, s25, v174
	v_lshl_add_u32 v44, s27, 2, v133
	ds_read_b128 v[32:35], v152
	ds_read_b128 v[64:67], v44 offset:2816
	ds_read_b128 v[68:71], v44 offset:2848
	ds_read_b128 v[72:75], v44 offset:2880
	ds_read_b128 v[76:79], v44 offset:2912
	ds_read_b128 v[36:39], v152 offset:4608
	ds_read_b128 v[40:43], v152 offset:32
	s_waitcnt lgkmcnt(2)
	v_mfma_f32_32x32x16_bf16 v[64:79], v[32:35], v[96:99], v[64:79]
	ds_read_b128 v[80:83], v44 offset:2944
	ds_read_b128 v[84:87], v44 offset:2976
	ds_read_b128 v[88:91], v44 offset:3008
	ds_read_b128 v[92:95], v44 offset:3040
	ds_read_b128 v[32:35], v152 offset:4640
	s_add_i32 s26, s26, 64
	s_cmp_lg_u32 s13, 0
	s_cselect_b32 s25, s26, 0xfffffd80
	v_lshl_add_u32 v60, s25, 2, v133
	v_add_u32_e32 v179, s24, v135
	s_waitcnt lgkmcnt(1)
	v_mfma_f32_32x32x16_bf16 v[64:79], v[40:43], v[100:103], v[64:79]
	v_mfma_f32_32x32x16_bf16 v[80:95], v[36:39], v[96:99], v[80:95]
	s_waitcnt lgkmcnt(0)
	v_mfma_f32_32x32x16_bf16 v[80:95], v[32:35], v[100:103], v[80:95]
	ds_read_b128 v[32:35], v152 offset:64
	ds_read_b128 v[36:39], v152 offset:96
	s_waitcnt lgkmcnt(1)
	v_mfma_f32_32x32x16_bf16 v[64:79], v[32:35], v[104:107], v[64:79]
	ds_read_b128 v[32:35], v152 offset:4672
	ds_read_b128 v[48:51], v152 offset:4704
	s_waitcnt lgkmcnt(1)
	v_mfma_f32_32x32x16_bf16 v[64:79], v[36:39], v[108:111], v[64:79]
	v_mfma_f32_32x32x16_bf16 v[80:95], v[32:35], v[104:107], v[80:95]
	ds_read_b128 v[32:35], v60 offset:2816
	ds_read_b128 v[36:39], v60 offset:2848
	ds_read_b128 v[40:43], v60 offset:2880
	ds_read_b128 v[44:47], v60 offset:2912
	ds_read_b128 v[140:143], v152 offset:9216
	s_nop 6
	v_exp_f32_e32 v168, v64
	s_waitcnt lgkmcnt(5)
	v_mfma_f32_32x32x16_bf16 v[80:95], v[48:51], v[108:111], v[80:95]
	ds_read_b128 v[48:51], v60 offset:2944
	ds_read_b128 v[52:55], v60 offset:2976
	ds_read_b128 v[56:59], v60 offset:3008
	ds_read_b128 v[60:63], v60 offset:3040
	ds_read_b128 v[144:147], v152 offset:9248
	ds_read_b128 v[148:151], v152 offset:13824
	ds_read_b128 v[180:183], v152 offset:13856
	ds_read_b128 v[184:187], v152 offset:9280
	ds_read_b128 v[188:191], v152 offset:9312
	ds_read_b128 v[192:195], v152 offset:13888
	ds_read_b128 v[196:199], v152 offset:13920
	v_exp_f32_e32 v156, v65
	v_exp_f32_e32 v158, v66
	v_exp_f32_e32 v162, v67
	v_exp_f32_e32 v216, v68
	v_exp_f32_e32 v76, v76
	s_waitcnt lgkmcnt(5)
	v_mfma_f32_32x32x16_bf16 v[48:63], v[148:151], v[96:99], v[48:63]
	v_exp_f32_e32 v148, v71
	v_exp_f32_e32 v170, v80
	v_exp_f32_e32 v164, v82
	v_exp_f32_e32 v150, v86
	v_exp_f32_e32 v80, v72
	v_exp_f32_e32 v82, v73
	v_exp_f32_e32 v86, v74
	s_waitcnt lgkmcnt(4)
	v_mfma_f32_32x32x16_bf16 v[48:63], v[180:183], v[100:103], v[48:63]
	v_cvt_pk_bf16_f32 v180, v168, v156
	v_cvt_pk_bf16_f32 v181, v158, v162
	v_exp_f32_e32 v64, v77
	v_exp_f32_e32 v66, v78
	v_exp_f32_e32 v160, v81
	v_exp_f32_e32 v166, v83
	v_exp_f32_e32 v172, v84
	v_mfma_f32_32x32x16_bf16 v[32:47], v[140:143], v[96:99], v[32:47]
	v_mfma_f32_32x32x16_bf16 v[32:47], v[144:147], v[100:103], v[32:47]
	v_exp_f32_e32 v140, v69
	v_exp_f32_e32 v142, v70
	v_exp_f32_e32 v70, v79
	v_exp_f32_e32 v154, v87
	v_cvt_pk_bf16_f32 v182, v216, v140
	v_cvt_pk_bf16_f32 v183, v142, v148
	v_exp_f32_e32 v84, v88
	s_waitcnt lgkmcnt(1)
	v_mfma_f32_32x32x16_bf16 v[48:63], v[192:195], v[104:107], v[48:63]
	ds_read_b64_tr_b16 v[192:193], v179 offset:36864
	ds_read_b64_tr_b16 v[194:195], v179 offset:38400
	ds_read_b64_tr_b16 v[202:203], v179 offset:38464
	ds_read_b64_tr_b16 v[200:201], v179 offset:36928
	v_exp_f32_e32 v88, v89
	v_exp_f32_e32 v152, v91
	v_exp_f32_e32 v92, v92
	v_exp_f32_e32 v68, v93
	v_exp_f32_e32 v72, v94
	v_exp_f32_e32 v146, v90
	v_exp_f32_e32 v90, v75
	v_exp_f32_e32 v144, v85
	v_exp_f32_e32 v74, v95
	s_waitcnt lgkmcnt(0)
	v_mfma_f32_32x32x16_bf16 v[16:31], v[200:203], v[180:183], v[16:31]
	v_mfma_f32_32x32x16_bf16 v[0:15], v[192:195], v[180:183], v[0:15]
	ds_read_b64_tr_b16 v[192:193], v179 offset:39936
	ds_read_b64_tr_b16 v[194:195], v179 offset:41472
	ds_read_b64_tr_b16 v[206:207], v179 offset:41536
	ds_read_b64_tr_b16 v[204:205], v179 offset:40000
	ds_read_b64_tr_b16 v[208:209], v179 offset:43008
	ds_read_b64_tr_b16 v[210:211], v179 offset:44544
	ds_read_b64_tr_b16 v[214:215], v179 offset:44608
	ds_read_b64_tr_b16 v[212:213], v179 offset:43072
	ds_read_b64_tr_b16 v[180:181], v179 offset:46080
	ds_read_b64_tr_b16 v[182:183], v179 offset:47616
	ds_read_b64_tr_b16 v[202:203], v179 offset:47680
	ds_read_b64_tr_b16 v[200:201], v179 offset:46144
	v_mfma_f32_32x32x16_bf16 v[32:47], v[184:187], v[104:107], v[32:47]
	v_cvt_pk_bf16_f32 v184, v80, v82
	v_cvt_pk_bf16_f32 v185, v86, v90
	v_cvt_pk_bf16_f32 v186, v76, v64
	v_cvt_pk_bf16_f32 v187, v66, v70
	s_waitcnt lgkmcnt(8)
	s_nop 0
	v_mfma_f32_32x32x16_bf16 v[16:31], v[204:207], v[184:187], v[16:31]
	v_mfma_f32_32x32x16_bf16 v[0:15], v[192:195], v[184:187], v[0:15]
	v_mfma_f32_32x32x16_bf16 v[32:47], v[188:191], v[108:111], v[32:47]
	v_cvt_pk_bf16_f32 v188, v170, v160
	v_cvt_pk_bf16_f32 v189, v164, v166
	v_cvt_pk_bf16_f32 v190, v172, v144
	v_cvt_pk_bf16_f32 v191, v150, v154
	s_waitcnt lgkmcnt(4)
	s_nop 0
	v_mfma_f32_32x32x16_bf16 v[16:31], v[212:215], v[188:191], v[16:31]
	s_nop 4
	v_exp_f32_e32 v169, v32
	v_exp_f32_e32 v157, v33
	v_exp_f32_e32 v159, v34
	v_exp_f32_e32 v217, v36
	v_exp_f32_e32 v163, v35
	v_exp_f32_e32 v141, v37
	v_exp_f32_e32 v143, v38
	v_mfma_f32_32x32x16_bf16 v[0:15], v[208:211], v[188:191], v[0:15]
	v_exp_f32_e32 v149, v39
	v_exp_f32_e32 v81, v40
	v_exp_f32_e32 v83, v41
	v_exp_f32_e32 v87, v42
	v_exp_f32_e32 v91, v43
	ds_read_b64_tr_b16 v[40:41], v179 offset:49152
	ds_read_b64_tr_b16 v[42:43], v179 offset:50688
	v_cvt_pk_bf16_f32 v32, v169, v157
	v_mfma_f32_32x32x16_bf16 v[48:63], v[196:199], v[108:111], v[48:63]
	v_cvt_pk_bf16_f32 v196, v84, v88
	v_cvt_pk_bf16_f32 v197, v146, v152
	v_cvt_pk_bf16_f32 v198, v92, v68
	v_cvt_pk_bf16_f32 v199, v72, v74
	v_cvt_pk_bf16_f32 v33, v159, v163
	v_cvt_pk_bf16_f32 v34, v217, v141
	v_cvt_pk_bf16_f32 v35, v143, v149
	s_waitcnt lgkmcnt(2)
	v_mfma_f32_32x32x16_bf16 v[16:31], v[200:203], v[196:199], v[16:31]
	s_nop 2
	v_exp_f32_e32 v171, v48
	v_exp_f32_e32 v161, v49
	v_exp_f32_e32 v165, v50
	v_exp_f32_e32 v167, v51
	ds_read_b64_tr_b16 v[50:51], v179 offset:50752
	ds_read_b64_tr_b16 v[48:49], v179 offset:49216
	v_exp_f32_e32 v85, v56
	v_exp_f32_e32 v89, v57
	v_mfma_f32_32x32x16_bf16 v[0:15], v[180:183], v[196:199], v[0:15]
	v_add_f32_e64 v56, v168, v170
	v_add_f32_e64 v57, v169, v171
	v_exp_f32_e32 v173, v52
	v_exp_f32_e32 v145, v53
	v_exp_f32_e32 v151, v54
	v_exp_f32_e32 v155, v55
	v_exp_f32_e32 v77, v44
	v_exp_f32_e32 v65, v45
	s_waitcnt lgkmcnt(0)
	v_mfma_f32_32x32x16_bf16 v[0:15], v[40:43], v[32:35], v[0:15]
	v_exp_f32_e32 v67, v46
	v_exp_f32_e32 v71, v47
	ds_read_b64_tr_b16 v[52:53], v179 offset:52224
	ds_read_b64_tr_b16 v[54:55], v179 offset:53760
	v_cvt_pk_bf16_f32 v36, v81, v83
	v_cvt_pk_bf16_f32 v37, v87, v91
	v_cvt_pk_bf16_f32 v38, v77, v65
	v_cvt_pk_bf16_f32 v39, v67, v71
	v_mfma_f32_32x32x16_bf16 v[16:31], v[48:51], v[32:35], v[16:31]
	v_add_f32_e64 v32, v156, v160
	v_add_f32_e64 v33, v157, v161
	v_add_f32_e32 v56, v32, v56
	v_add_f32_e32 v57, v33, v57
	v_add_f32_e64 v48, v158, v164
	v_add_f32_e64 v49, v159, v165
	ds_read_b64_tr_b16 v[34:35], v179 offset:53824
	ds_read_b64_tr_b16 v[32:33], v179 offset:52288
	v_add_f32_e32 v50, v162, v166
	v_add_f32_e32 v51, v163, v167
	v_add_f32_e32 v48, v48, v56
	v_add_f32_e32 v49, v49, v57
	s_waitcnt lgkmcnt(0)
	v_mfma_f32_32x32x16_bf16 v[16:31], v[32:35], v[36:39], v[16:31]
	v_add_f32_e64 v78, v216, v172
	v_add_f32_e64 v79, v217, v173
	v_exp_f32_e32 v147, v58
	v_cvt_pk_bf16_f32 v44, v171, v161
	v_cvt_pk_bf16_f32 v45, v165, v167
	v_cvt_pk_bf16_f32 v46, v173, v145
	v_cvt_pk_bf16_f32 v47, v151, v155
	v_add_f32_e32 v56, v142, v150
	v_add_f32_e32 v57, v143, v151
	v_mfma_f32_32x32x16_bf16 v[0:15], v[52:55], v[36:39], v[0:15]
	v_add_f32_e64 v52, v50, v48
	v_add_f32_e64 v53, v51, v49
	ds_read_b64_tr_b16 v[48:49], v179 offset:55296
	ds_read_b64_tr_b16 v[50:51], v179 offset:56832
	ds_read_b64_tr_b16 v[34:35], v179 offset:56896
	ds_read_b64_tr_b16 v[32:33], v179 offset:55360
	v_add_f32_e32 v54, v140, v144
	v_add_f32_e32 v55, v141, v145
	v_add_f32_e32 v36, v78, v52
	v_add_f32_e32 v37, v79, v53
	v_exp_f32_e32 v153, v59
	v_add_f32_e32 v52, v54, v36
	v_add_f32_e32 v53, v55, v37
	v_add_f32_e32 v58, v148, v154
	v_add_f32_e32 v59, v149, v155
	s_waitcnt lgkmcnt(0)
	v_mfma_f32_32x32x16_bf16 v[16:31], v[32:35], v[44:47], v[16:31]
	v_add_f32_e64 v32, v56, v52
	v_add_f32_e64 v33, v57, v53
	v_exp_f32_e32 v93, v60
	v_exp_f32_e32 v69, v61
	v_add_f32_e32 v60, v80, v84
	v_add_f32_e32 v61, v81, v85
	v_add_f32_e32 v32, v58, v32
	v_add_f32_e32 v33, v59, v33
	v_exp_f32_e32 v73, v62
	v_exp_f32_e32 v75, v63
	v_mfma_f32_32x32x16_bf16 v[0:15], v[48:51], v[44:47], v[0:15]
	v_add_f32_e64 v62, v82, v88
	v_add_f32_e64 v63, v83, v89
	v_add_f32_e64 v32, v60, v32
	v_add_f32_e64 v33, v61, v33
	v_add_f32_e64 v80, v86, v146
	v_add_f32_e64 v81, v87, v147
	v_add_f32_e32 v32, v62, v32
	v_add_f32_e32 v33, v63, v33
	ds_read_b64_tr_b16 v[36:37], v179 offset:58368
	ds_read_b64_tr_b16 v[38:39], v179 offset:59904
	v_add_f32_e32 v44, v80, v32
	v_add_f32_e32 v45, v81, v33
	ds_read_b64_tr_b16 v[34:35], v179 offset:59968
	ds_read_b64_tr_b16 v[32:33], v179 offset:58432
	v_cvt_pk_bf16_f32 v40, v85, v89
	v_cvt_pk_bf16_f32 v41, v147, v153
	v_cvt_pk_bf16_f32 v42, v93, v69
	v_cvt_pk_bf16_f32 v43, v73, v75
	v_add_f32_e32 v82, v90, v152
	v_add_f32_e32 v83, v91, v153
	v_add_f32_e32 v76, v76, v92
	v_add_f32_e32 v77, v77, v93
	s_waitcnt lgkmcnt(2)
	v_mfma_f32_32x32x16_bf16 v[0:15], v[36:39], v[40:43], v[0:15]
	v_add_f32_e64 v36, v82, v44
	v_add_f32_e64 v37, v83, v45
	v_add_f32_e64 v48, v64, v68
	v_add_f32_e64 v49, v65, v69
	v_add_f32_e64 v36, v76, v36
	v_add_f32_e64 v37, v77, v37
	v_add_f32_e32 v50, v66, v72
	v_add_f32_e32 v51, v67, v73
	v_add_f32_e32 v36, v48, v36
	v_add_f32_e32 v37, v49, v37
	v_add_f32_e32 v64, v70, v74
	v_add_f32_e32 v65, v71, v75
	v_add_f32_e32 v36, v50, v36
	v_add_f32_e32 v37, v51, v37
	s_waitcnt lgkmcnt(0)
	v_mfma_f32_32x32x16_bf16 v[16:31], v[32:35], v[40:43], v[16:31]
	v_add_f32_e64 v36, v64, v36
	v_add_f32_e64 v37, v65, v37
	v_add_f32_e32 v36, v178, v36
	v_add_f32_e32 v178, v36, v37
	s_branch .LBB0_1072
